# causal-band bias adds: eight table reads kept in flight in the dead K-fragment registers instead of one read + full LDS wait per pair
# speedup vs baseline: 1.0133x; 1.0057x over previous
; __device__ __forceinline__ void cmask(f32x16&p0,f32x16&p1,int jb,int qrel,int hi,const __attribute__((address_space(3))) float*tab){
;   asm volatile("s_nop 15\n\ts_nop 7":"+v"(p0),"+v"(p1));
;   const __attribute__((address_space(3))) float*tp=tab+(qrel-64*jb-4*hi+256);
;   #pragma unroll
;   for(int r=0;r<16;++r){const int o=(r&3)+8*(r>>2); float a0=tp[-o], a1=tp[-o-32]; asm volatile("v_add_f32_e32 %0, %1, %0":"+v"(p0[r]):"v"(a0)); asm volatile("v_add_f32_e32 %0, %1, %0":"+v"(p1[r]):"v"(a1));}
; }
.LBB0_391:
	v_add_u32_e32 v0, s96, v232
	ds_read_b64_tr_b16 v[6:7], v0 offset:24576
	ds_read_b64_tr_b16 v[8:9], v0 offset:25088
	s_waitcnt lgkmcnt(9)
	v_mfma_f32_32x32x16_bf16 v[96:111], v[188:191], v[156:159], v[48:63]
	v_add_f32_e32 v2, v80, v81
	v_add_f32_e32 v2, v82, v2
	v_add_f32_e32 v2, v83, v2
	v_add_f32_e32 v2, v84, v2
	v_add_f32_e32 v10, v85, v2
	v_cvt_pk_bf16_f32 v140, v80, v81
	v_cvt_pk_bf16_f32 v141, v82, v83
	ds_read_b64_tr_b16 v[2:3], v0 offset:28672
	ds_read_b64_tr_b16 v[4:5], v0 offset:29184
	s_waitcnt lgkmcnt(10)
	v_mfma_f32_32x32x16_bf16 v[48:63], v[184:187], v[156:159], v[48:63]
	v_add_f32_e32 v10, v86, v10
	v_add_f32_e32 v10, v87, v10
	v_add_f32_e32 v10, v88, v10
	v_add_f32_e32 v14, v89, v10
	v_cvt_pk_bf16_f32 v142, v84, v85
	v_cvt_pk_bf16_f32 v143, v86, v87
	ds_read_b64_tr_b16 v[10:11], v0 offset:25600
	ds_read_b64_tr_b16 v[12:13], v0 offset:26112
	s_waitcnt lgkmcnt(11)
	v_mfma_f32_32x32x16_bf16 v[96:111], v[180:183], v[152:155], v[96:111]
	v_add_f32_e32 v14, v90, v14
	v_add_f32_e32 v14, v91, v14
	v_add_f32_e32 v14, v92, v14
	v_add_f32_e32 v14, v93, v14
	v_cvt_pk_bf16_f32 v136, v88, v89
	v_cvt_pk_bf16_f32 v137, v90, v91
	ds_read_b64_tr_b16 v[84:85], v0 offset:29696
	ds_read_b64_tr_b16 v[86:87], v0 offset:30208
	s_waitcnt lgkmcnt(12)
	v_mfma_f32_32x32x16_bf16 v[48:63], v[176:179], v[152:155], v[48:63]
	v_add_f32_e32 v14, v94, v14
	v_add_f32_e32 v14, v95, v14
	v_add_f32_e32 v14, v64, v14
	v_add_f32_e32 v14, v65, v14
	v_cvt_pk_bf16_f32 v138, v92, v93
	v_cvt_pk_bf16_f32 v139, v94, v95
	ds_read_b64_tr_b16 v[80:81], v0 offset:26624
	ds_read_b64_tr_b16 v[82:83], v0 offset:27136
	s_waitcnt lgkmcnt(13)
	v_mfma_f32_32x32x16_bf16 v[96:111], v[172:175], v[148:151], v[96:111]
	v_add_f32_e32 v14, v66, v14
	v_add_f32_e32 v14, v67, v14
	v_add_f32_e32 v14, v68, v14
	v_add_f32_e32 v14, v69, v14
	v_cvt_pk_bf16_f32 v132, v64, v65
	v_cvt_pk_bf16_f32 v133, v66, v67
	ds_read_b64_tr_b16 v[88:89], v0 offset:30720
	ds_read_b64_tr_b16 v[90:91], v0 offset:31232
	s_waitcnt lgkmcnt(14)
	v_mfma_f32_32x32x16_bf16 v[48:63], v[168:171], v[148:151], v[48:63]
	v_add_f32_e32 v14, v70, v14
	v_add_f32_e32 v14, v71, v14
	v_add_f32_e32 v14, v72, v14
	v_add_f32_e32 v14, v73, v14
	v_cvt_pk_bf16_f32 v134, v68, v69
	v_cvt_pk_bf16_f32 v135, v70, v71
	ds_read_b64_tr_b16 v[92:93], v0 offset:27648
	ds_read_b64_tr_b16 v[94:95], v0 offset:28160
	s_waitcnt lgkmcnt(14)
	v_mfma_f32_32x32x16_bf16 v[96:111], v[164:167], v[144:147], v[96:111]
	v_add_f32_e32 v14, v74, v14
	v_add_f32_e32 v14, v75, v14
	v_add_f32_e32 v14, v76, v14
	v_add_f32_e32 v14, v77, v14
	v_cvt_pk_bf16_f32 v128, v72, v73
	v_cvt_pk_bf16_f32 v129, v74, v75
	ds_read_b64_tr_b16 v[112:113], v0 offset:31744
	ds_read_b64_tr_b16 v[114:115], v0 offset:32256
	v_mfma_f32_32x32x16_bf16 v[48:63], v[160:163], v[144:147], v[48:63]
	v_add_f32_e32 v0, v78, v14
	v_add_f32_e32 v0, v79, v0
	v_add_f32_e32 v0, 0, v0
	v_cvt_pk_bf16_f32 v130, v76, v77
	v_cvt_pk_bf16_f32 v131, v78, v79
	v_lshl_add_u32 v14, v230, 2, 0
	v_add_u32_e32 v64, 0xc800, v14
	s_nop 15
	s_nop 7
	s_waitcnt lgkmcnt(7)
	ds_read2_b32 v[176:177], v64 offset0:32 offset1:64
	ds_read2_b32 v[178:179], v64 offset0:31 offset1:63
	ds_read2_b32 v[180:181], v64 offset0:30 offset1:62
	ds_read2_b32 v[182:183], v64 offset0:29 offset1:61
	ds_read2_b32 v[184:185], v64 offset0:24 offset1:56
	ds_read2_b32 v[186:187], v64 offset0:23 offset1:55
	ds_read2_b32 v[188:189], v64 offset0:22 offset1:54
	ds_read2_b32 v[190:191], v64 offset0:21 offset1:53
	s_waitcnt lgkmcnt(7)
	v_add_f32_e32 v96, v177, v96
	v_add_f32_e32 v48, v176, v48
	ds_read2_b32 v[176:177], v64 offset0:16 offset1:48
	s_waitcnt lgkmcnt(7)
	v_add_f32_e32 v97, v179, v97
	v_add_f32_e32 v49, v178, v49
	ds_read2_b32 v[178:179], v64 offset0:15 offset1:47
	s_waitcnt lgkmcnt(7)
	v_add_f32_e32 v98, v181, v98
	v_add_f32_e32 v50, v180, v50
	ds_read2_b32 v[180:181], v64 offset0:14 offset1:46
	s_waitcnt lgkmcnt(7)
	v_add_f32_e32 v99, v183, v99
	v_add_f32_e32 v51, v182, v51
	ds_read2_b32 v[182:183], v64 offset0:13 offset1:45
	s_waitcnt lgkmcnt(7)
	v_add_f32_e32 v100, v185, v100
	v_add_f32_e32 v52, v184, v52
	ds_read2_b32 v[184:185], v64 offset0:8 offset1:40
	s_waitcnt lgkmcnt(7)
	v_add_f32_e32 v101, v187, v101
	v_add_f32_e32 v53, v186, v53
	ds_read2_b32 v[186:187], v64 offset0:7 offset1:39
	s_waitcnt lgkmcnt(7)
	v_add_f32_e32 v102, v189, v102
	v_add_f32_e32 v54, v188, v54
	ds_read2_b32 v[188:189], v64 offset0:6 offset1:38
	s_waitcnt lgkmcnt(7)
	v_add_f32_e32 v103, v191, v103
	v_add_f32_e32 v55, v190, v55
	ds_read2_b32 v[190:191], v64 offset0:5 offset1:37
	s_waitcnt lgkmcnt(7)
	v_add_f32_e32 v104, v177, v104
	v_add_f32_e32 v56, v176, v56
	s_waitcnt lgkmcnt(6)
	v_add_f32_e32 v105, v179, v105
	v_add_f32_e32 v57, v178, v57
	s_waitcnt lgkmcnt(5)
	v_add_f32_e32 v106, v181, v106
	v_add_f32_e32 v58, v180, v58
	s_waitcnt lgkmcnt(4)
	v_add_f32_e32 v107, v183, v107
	v_add_f32_e32 v59, v182, v59
	s_waitcnt lgkmcnt(3)
	v_add_f32_e32 v108, v185, v108
	v_add_f32_e32 v60, v184, v60
	s_waitcnt lgkmcnt(2)
	v_add_f32_e32 v109, v187, v109
	v_add_f32_e32 v61, v186, v61
	s_waitcnt lgkmcnt(1)
	v_add_f32_e32 v110, v189, v110
	v_add_f32_e32 v62, v188, v62
	s_waitcnt lgkmcnt(0)
	v_add_f32_e32 v111, v191, v111
	v_add_f32_e32 v63, v190, v63
	v_max_f32_e32 v14, v96, v96
	v_max_f32_e32 v15, v97, v97
	v_max_f32_e32 v14, v14, v15
	v_max3_f32 v15, v98, v99, v49
	v_max3_f32 v14, v14, v48, v50
	v_max3_f32 v14, v14, v51, v100
	v_max3_f32 v15, v15, v102, v103
	v_max3_f32 v14, v14, v101, v52
	v_max3_f32 v15, v15, v54, v55
	v_max3_f32 v14, v14, v53, v104
	v_max3_f32 v15, v15, v106, v107
	v_max3_f32 v14, v14, v105, v56
	v_max3_f32 v15, v15, v58, v59
	v_max3_f32 v14, v14, v57, v108
	v_max3_f32 v15, v15, v110, v111
	v_max3_f32 v14, v14, v109, v60
	v_max3_f32 v15, v15, v62, v63
	v_max3_f32 v14, v14, v61, v15
	v_mov_b32_e32 v15, v14
	s_nop 1
	v_permlane32_swap_b32_e32 v14, v15
	v_max_f32_e32 v15, v15, v15
	v_max_f32_e32 v14, v14, v14
	v_max_f32_e32 v14, v14, v15
	v_cmp_lt_f32_e32 vcc, s21, v14
	s_cmp_lg_u64 vcc, 0
	v_add_f32_e32 v0, v234, v0
	s_cselect_b64 s[6:7], -1, 0
	s_cbranch_vccnz .LBB0_446

; __device__ __forceinline__ void cmask(f32x16&p0,f32x16&p1,int jb,int qrel,int hi,const __attribute__((address_space(3))) float*tab){
;   asm volatile("s_nop 15\n\ts_nop 7":"+v"(p0),"+v"(p1));
;   const __attribute__((address_space(3))) float*tp=tab+(qrel-64*jb-4*hi+256);
;   #pragma unroll
;   for(int r=0;r<16;++r){const int o=(r&3)+8*(r>>2); float a0=tp[-o], a1=tp[-o-32]; asm volatile("v_add_f32_e32 %0, %1, %0":"+v"(p0[r]):"v"(a0)); asm volatile("v_add_f32_e32 %0, %1, %0":"+v"(p1[r]):"v"(a1));}
; }
.LBB0_400:
	v_lshl_add_u64 v[14:15], v[212:213], 0, s[84:85]
	v_lshl_add_u64 v[76:77], v[14:15], 0, s[22:23]
	s_add_i32 s8, s96, s95
	s_mov_b32 s9, m0
	s_mov_b32 m0, s8
	s_nop 0
	global_load_lds_dwordx4 v[76:77], off
	s_mov_b32 m0, s9
	s_add_i32 s91, s20, s90
	s_add_i32 s8, s91, -2
	s_cmp_lt_i32 s8, -2
	v_add_u32_e32 v237, s12, v235
	s_cbranch_scc1 .LBB0_402
	v_add_u32_e32 v76, 0xca00, v237
	s_nop 15
	s_nop 7
	v_add_u32_e32 v78, 0xc800, v237
	s_waitcnt lgkmcnt(7)
	ds_read2_b32 v[176:177], v76 offset0:96 offset1:128
	ds_read2_b32 v[178:179], v78 offset0:223 offset1:255
	ds_read2_b32 v[180:181], v78 offset0:222 offset1:254
	ds_read2_b32 v[182:183], v78 offset0:221 offset1:253
	ds_read2_b32 v[184:185], v78 offset0:216 offset1:248
	ds_read2_b32 v[186:187], v78 offset0:215 offset1:247
	ds_read2_b32 v[188:189], v78 offset0:214 offset1:246
	ds_read2_b32 v[190:191], v78 offset0:213 offset1:245
	s_waitcnt lgkmcnt(7)
	v_add_f32_e32 v112, v177, v112
	v_add_f32_e32 v96, v176, v96
	ds_read2_b32 v[176:177], v78 offset0:208 offset1:240
	s_waitcnt lgkmcnt(7)
	v_add_f32_e32 v113, v179, v113
	v_add_f32_e32 v97, v178, v97
	ds_read2_b32 v[178:179], v78 offset0:207 offset1:239
	s_waitcnt lgkmcnt(7)
	v_add_f32_e32 v114, v181, v114
	v_add_f32_e32 v98, v180, v98
	ds_read2_b32 v[180:181], v78 offset0:206 offset1:238
	s_waitcnt lgkmcnt(7)
	v_add_f32_e32 v115, v183, v115
	v_add_f32_e32 v99, v182, v99
	ds_read2_b32 v[182:183], v78 offset0:205 offset1:237
	s_waitcnt lgkmcnt(7)
	v_add_f32_e32 v116, v185, v116
	v_add_f32_e32 v100, v184, v100
	ds_read2_b32 v[184:185], v78 offset0:200 offset1:232
	s_waitcnt lgkmcnt(7)
	v_add_f32_e32 v117, v187, v117
	v_add_f32_e32 v101, v186, v101
	ds_read2_b32 v[186:187], v78 offset0:199 offset1:231
	s_waitcnt lgkmcnt(7)
	v_add_f32_e32 v118, v189, v118
	v_add_f32_e32 v102, v188, v102
	ds_read2_b32 v[188:189], v78 offset0:198 offset1:230
	s_waitcnt lgkmcnt(7)
	v_add_f32_e32 v119, v191, v119
	v_add_f32_e32 v103, v190, v103
	ds_read2_b32 v[190:191], v78 offset0:197 offset1:229
	s_waitcnt lgkmcnt(7)
	v_add_f32_e32 v120, v177, v120
	v_add_f32_e32 v104, v176, v104
	s_waitcnt lgkmcnt(6)
	v_add_f32_e32 v121, v179, v121
	v_add_f32_e32 v105, v178, v105
	s_waitcnt lgkmcnt(5)
	v_add_f32_e32 v122, v181, v122
	v_add_f32_e32 v106, v180, v106
	s_waitcnt lgkmcnt(4)
	v_add_f32_e32 v123, v183, v123
	v_add_f32_e32 v107, v182, v107
	s_waitcnt lgkmcnt(3)
	v_add_f32_e32 v124, v185, v124
	v_add_f32_e32 v108, v184, v108
	s_waitcnt lgkmcnt(2)
	v_add_f32_e32 v125, v187, v125
	v_add_f32_e32 v109, v186, v109
	s_waitcnt lgkmcnt(1)
	v_add_f32_e32 v126, v189, v126
	v_add_f32_e32 v110, v188, v110
	s_waitcnt lgkmcnt(0)
	v_add_f32_e32 v127, v191, v127
	v_add_f32_e32 v111, v190, v111

; __device__ __forceinline__ void cmask(f32x16&p0,f32x16&p1,int jb,int qrel,int hi,const __attribute__((address_space(3))) float*tab){
;   asm volatile("s_nop 15\n\ts_nop 7":"+v"(p0),"+v"(p1));
;   const __attribute__((address_space(3))) float*tp=tab+(qrel-64*jb-4*hi+256);
;   #pragma unroll
;   for(int r=0;r<16;++r){const int o=(r&3)+8*(r>>2); float a0=tp[-o], a1=tp[-o-32]; asm volatile("v_add_f32_e32 %0, %1, %0":"+v"(p0[r]):"v"(a0)); asm volatile("v_add_f32_e32 %0, %1, %0":"+v"(p1[r]):"v"(a1));}
; }
.LBB0_415:
	s_add_i32 s91, s91, -1
	s_cmp_lt_i32 s91, -2
	s_cbranch_scc1 .LBB0_417
	v_add_u32_e32 v97, 0xc800, v237
	s_nop 15
	s_nop 7
	s_waitcnt lgkmcnt(7)
	ds_read2_b32 v[176:177], v97 offset0:160 offset1:192
	ds_read2_b32 v[178:179], v97 offset0:159 offset1:191
	ds_read2_b32 v[180:181], v97 offset0:158 offset1:190
	ds_read2_b32 v[182:183], v97 offset0:157 offset1:189
	ds_read2_b32 v[184:185], v97 offset0:152 offset1:184
	ds_read2_b32 v[186:187], v97 offset0:151 offset1:183
	ds_read2_b32 v[188:189], v97 offset0:150 offset1:182
	ds_read2_b32 v[190:191], v97 offset0:149 offset1:181
	s_waitcnt lgkmcnt(7)
	v_add_f32_e32 v80, v177, v80
	v_add_f32_e32 v64, v176, v64
	ds_read2_b32 v[176:177], v97 offset0:144 offset1:176
	s_waitcnt lgkmcnt(7)
	v_add_f32_e32 v81, v179, v81
	v_add_f32_e32 v65, v178, v65
	ds_read2_b32 v[178:179], v97 offset0:143 offset1:175
	s_waitcnt lgkmcnt(7)
	v_add_f32_e32 v82, v181, v82
	v_add_f32_e32 v66, v180, v66
	ds_read2_b32 v[180:181], v97 offset0:142 offset1:174
	s_waitcnt lgkmcnt(7)
	v_add_f32_e32 v83, v183, v83
	v_add_f32_e32 v67, v182, v67
	ds_read2_b32 v[182:183], v97 offset0:141 offset1:173
	s_waitcnt lgkmcnt(7)
	v_add_f32_e32 v84, v185, v84
	v_add_f32_e32 v68, v184, v68
	ds_read2_b32 v[184:185], v97 offset0:136 offset1:168
	s_waitcnt lgkmcnt(7)
	v_add_f32_e32 v85, v187, v85
	v_add_f32_e32 v69, v186, v69
	ds_read2_b32 v[186:187], v97 offset0:135 offset1:167
	s_waitcnt lgkmcnt(7)
	v_add_f32_e32 v86, v189, v86
	v_add_f32_e32 v70, v188, v70
	ds_read2_b32 v[188:189], v97 offset0:134 offset1:166
	s_waitcnt lgkmcnt(7)
	v_add_f32_e32 v87, v191, v87
	v_add_f32_e32 v71, v190, v71
	ds_read2_b32 v[190:191], v97 offset0:133 offset1:165
	s_waitcnt lgkmcnt(7)
	v_add_f32_e32 v88, v177, v88
	v_add_f32_e32 v72, v176, v72
	s_waitcnt lgkmcnt(6)
	v_add_f32_e32 v89, v179, v89
	v_add_f32_e32 v73, v178, v73
	s_waitcnt lgkmcnt(5)
	v_add_f32_e32 v90, v181, v90
	v_add_f32_e32 v74, v180, v74
	s_waitcnt lgkmcnt(4)
	v_add_f32_e32 v91, v183, v91
	v_add_f32_e32 v75, v182, v75
	s_waitcnt lgkmcnt(3)
	v_add_f32_e32 v92, v185, v92
	v_add_f32_e32 v76, v184, v76
	s_waitcnt lgkmcnt(2)
	v_add_f32_e32 v93, v187, v93
	v_add_f32_e32 v77, v186, v77
	s_waitcnt lgkmcnt(1)
	v_add_f32_e32 v94, v189, v94
	v_add_f32_e32 v78, v188, v78
	s_waitcnt lgkmcnt(0)
	v_add_f32_e32 v95, v191, v95
	v_add_f32_e32 v79, v190, v79
